# GLA recurrence: loop-invariant o_norm gains loaded once before the chunk loop; counted waits for the state-increment prefetch
# speedup vs baseline: 1.0033x; 1.0013x over previous
; #define LAS __attribute__((address_space(3)))
; __device__ __forceinline__ void gla_seq_unit(LAS unsigned char* lds, int b, int h, unsigned char* ws, const float* o_norm, bool dry) {
;     int tid_ = threadIdx.x; asm volatile("" : "+v"(tid_));
;     const int tid = tid_, wid = __builtin_amdgcn_readfirstlane(tid >> 6), lane = tid & 63, fr = lane & 15, fq = lane >> 4;
;     LAS float* PART = (LAS float*)lds;
;     LAS bf16_t* QDFL = (LAS bf16_t*)(lds + 2048);
;     LAS float* DECL = (LAS float*)(lds + 2048 + 16384);
;     bf16_t* GR = (bf16_t*)(ws + Z_GR);
;     f32x4 S[8][2];
; #pragma unroll
;     for (int i = 0; i < 8; ++i) { S[i][0] = (f32x4){0.f, 0.f, 0.f, 0.f}; S[i][1] = (f32x4){0.f, 0.f, 0.f, 0.f}; }
;     u32x4 ucp[8];
;     { const bf16_t* UC0 = (const bf16_t*)(ws + WS_UC) + (size_t)((b * 4 + h) * 32) * 32768;
; #pragma unroll
;       for (int mt = 0; mt < 6; ++mt) ucp[mt] = *(const u32x4*)(UC0 + ((wid * 8 + mt) * 64 + lane) * 8); }
;     ...
;                 const u32x2 rr = rr8[tt][vt]; const f32x4 on = *(const f32x4*)(o_norm + h * 256 + vcol);
.LBB0_284:
	s_and_b64 vcc, exec, s[2:3]
	s_mov_b64 s[30:31], 0x4000
	s_mov_b64 s[42:43], 0x10000
	s_cbranch_vccz .LBB0_297
	s_load_dwordx2 s[2:3], s[76:77], 0x70
	s_lshl_b32 s4, s78, 10
	s_ashr_i32 s5, s4, 31
	s_ashr_i32 s16, s39, 2
	s_and_b32 s17, s39, 3
	s_lshl_b64 s[4:5], s[4:5], 2
	s_waitcnt lgkmcnt(0)
	s_add_u32 s18, s2, s4
	s_addc_u32 s19, s3, s5
	v_mov_b32_e32 v10, v238
	s_lshl_b32 s2, s16, 7
	s_lshl_b32 s3, s17, 5
	s_or_b32 s10, s3, s2
	v_readfirstlane_b32 s24, v10
	v_and_b32_e32 v11, 63, v10
	s_ashr_i32 s25, s24, 6
	s_ashr_i32 s11, s10, 31
	v_lshlrev_b32_e32 v13, 3, v11
	s_lshl_b64 s[12:13], s[10:11], 16
	v_lshl_or_b32 v0, s25, 12, v13
	s_add_u32 s2, s88, s12
	v_ashrrev_i32_e32 v1, 31, v0
	s_addc_u32 s3, s89, s13
	v_lshlrev_b64 v[2:3], 1, v[0:1]
	v_lshl_add_u64 v[4:5], s[2:3], 0, v[2:3]
	global_load_dwordx4 v[68:71], v[4:5], off
	global_load_dwordx4 v[64:67], v[4:5], off offset:1024
	global_load_dwordx4 v[60:63], v[4:5], off offset:2048
	global_load_dwordx4 v[52:55], v[4:5], off offset:3072
	v_or_b32_e32 v4, 0x800, v0
	v_ashrrev_i32_e32 v5, 31, v4
	v_or_b32_e32 v0, 0xa00, v0
	v_lshlrev_b64 v[4:5], 1, v[4:5]
	v_ashrrev_i32_e32 v1, 31, v0
	v_lshl_add_u64 v[6:7], s[2:3], 0, v[4:5]
	v_lshlrev_b64 v[0:1], 1, v[0:1]
	v_lshl_add_u64 v[8:9], s[2:3], 0, v[0:1]
	global_load_dwordx4 v[56:59], v[6:7], off
	global_load_dwordx4 v[44:47], v[8:9], off
	s_lshl_b32 s2, s17, 9
	s_add_u32 s2, s22, s2
	s_addc_u32 s3, s23, 0
	s_add_u32 s2, s2, 0x1a7a9000
	s_addc_u32 s3, s3, 0
	s_lshl_b32 s14, s25, 5
	s_ashr_i32 s15, s14, 31
	s_lshl_b64 s[4:5], s[14:15], 1
	v_lshrrev_b32_e32 v15, 2, v10
	s_add_u32 s4, s2, s4
	v_and_b32_e32 v15, 12, v15
	s_addc_u32 s5, s3, s5
	v_lshlrev_b32_e32 v160, 1, v15
	v_lshl_add_u64 v[120:121], s[4:5], 0, v[160:161]
	s_movk_i32 s4, 0x80
	v_and_b32_e32 v12, 15, v10
	v_lshlrev_b32_e32 v6, 3, v10
	v_and_b32_e32 v14, 0x7f, v10
	v_lshl_add_u32 v160, v10, 4, 0
	v_cmp_gt_i32_e64 s[4:5], s4, v10
	v_mul_lo_u32 v16, v10, -12
	v_and_b32_e32 v18, 48, v10
	s_and_b32 s15, s24, 0x3fffffc0
	v_or_b32_e32 v10, s14, v15
	s_lshl_b32 s14, s17, 10
	v_lshl_add_u32 v245, v12, 2, 0
	v_lshlrev_b32_e32 v17, 4, v11
	v_cmp_gt_u32_e64 s[6:7], 16, v11
	s_add_u32 s14, s18, s14
	v_ashrrev_i32_e32 v11, 31, v10
	v_lshl_add_u32 v246, s15, 2, v245
	s_addc_u32 s15, s19, 0
	v_lshl_add_u64 v[124:125], v[10:11], 1, s[2:3]
	s_lshl_b64 s[2:3], s[10:11], 9
	s_add_u32 s2, s2, 0x3b7a9000
	s_addc_u32 s3, s3, 0
	v_lshl_or_b32 v126, v14, 2, s2
	v_mov_b32_e32 v127, s3
	s_lshl_b64 s[2:3], s[10:11], 14
	v_add_u32_e32 v8, 0x1000, v6
	s_add_u32 s2, s2, 0x3a7a9000
	v_ashrrev_i32_e32 v7, 31, v6
	v_ashrrev_i32_e32 v9, 31, v8
	s_addc_u32 s3, s3, 0
	v_lshl_add_u64 v[128:129], v[6:7], 1, s[2:3]
	v_lshl_add_u64 v[130:131], v[8:9], 1, s[2:3]
	s_add_u32 s2, s12, 0x327a9000
	s_addc_u32 s3, s13, 0
	v_lshl_add_u64 v[136:137], s[2:3], 0, v[0:1]
	v_lshl_or_b32 v0, s25, 11, v13
	v_lshl_add_u64 v[134:135], s[2:3], 0, v[4:5]
	s_lshl_b64 s[2:3], s[10:11], 15
	v_ashrrev_i32_e32 v1, 31, v0
	v_mov_b32_e32 v140, 0
	v_lshl_add_u64 v[122:123], v[10:11], 2, s[14:15]
	global_load_dwordx4 v[162:165], v[122:123], off
	global_load_dwordx2 v[168:169], v[122:123], off offset:64
	global_load_dwordx2 v[242:243], v[122:123], off offset:72
	v_lshl_or_b32 v247, s16, 11, v12
	v_lshl_add_u64 v[132:133], s[12:13], 0, v[2:3]
	v_lshl_add_u64 v[138:139], v[0:1], 1, s[2:3]
	s_mov_b32 s10, 0
	v_add_u32_e32 v248, v160, v16
	v_add_u32_e32 v249, 0, v17
	v_add_u32_e32 v250, 0, v18
	v_mov_b32_e32 v141, v140
	v_mov_b32_e32 v142, v140
	v_mov_b32_e32 v143, v140
	v_mov_b32_e32 v144, v140
	v_mov_b32_e32 v145, v140
	v_mov_b32_e32 v146, v140
	v_mov_b32_e32 v147, v140
	v_mov_b32_e32 v148, v140
	v_mov_b32_e32 v149, v140
	v_mov_b32_e32 v150, v140
	v_mov_b32_e32 v151, v140
	v_mov_b32_e32 v152, v140
	v_mov_b32_e32 v153, v140
	v_mov_b32_e32 v154, v140
	v_mov_b32_e32 v155, v140
	v_mov_b32_e32 v156, v140
	v_mov_b32_e32 v157, v140
	v_mov_b32_e32 v158, v140
	v_mov_b32_e32 v159, v140
	v_mov_b32_e32 v170, v140
	v_mov_b32_e32 v171, v140
	v_mov_b32_e32 v172, v140
	v_mov_b32_e32 v173, v140
	v_mov_b32_e32 v174, v140
	v_mov_b32_e32 v175, v140
	v_mov_b32_e32 v176, v140
	v_mov_b32_e32 v177, v140
	v_mov_b32_e32 v178, v140
	v_mov_b32_e32 v179, v140
	v_mov_b32_e32 v180, v140
	v_mov_b32_e32 v181, v140
	v_mov_b32_e32 v182, v140
	v_mov_b32_e32 v183, v140
	v_mov_b32_e32 v184, v140
	v_mov_b32_e32 v185, v140
	v_mov_b32_e32 v186, v140
	v_mov_b32_e32 v187, v140
	v_mov_b32_e32 v188, v140
	v_mov_b32_e32 v189, v140
	v_mov_b32_e32 v190, v140
	v_mov_b32_e32 v191, v140
	v_mov_b32_e32 v192, v140
	v_mov_b32_e32 v193, v140
	v_mov_b32_e32 v194, v140
	v_mov_b32_e32 v195, v140
	v_mov_b32_e32 v196, v140
	v_mov_b32_e32 v197, v140
	v_mov_b32_e32 v198, v140
	v_mov_b32_e32 v199, v140
	v_mov_b32_e32 v200, v140
	v_mov_b32_e32 v201, v140
	v_mov_b32_e32 v202, v140
	v_mov_b32_e32 v203, v140
	v_mov_b32_e32 v204, v140
	v_mov_b32_e32 v205, v140
	v_mov_b32_e32 v206, v140
	v_mov_b32_e32 v207, v140
	v_mov_b32_e32 v208, v140
	v_mov_b32_e32 v209, v140
	v_mov_b32_e32 v210, v140
	v_mov_b32_e32 v211, v140
	v_mov_b32_e32 v212, v140
	v_mov_b32_e32 v213, v140
	s_branch .LBB0_287
; #define LAS __attribute__((address_space(3)))
; __device__ __forceinline__ unsigned cvt_pk_bf16(float lo, float hi) { const f32x2_t v = {lo, hi}; const bf16x2_t b = __builtin_convertvector(v, bf16x2_t); return __builtin_bit_cast(unsigned, b); }
; __device__ __forceinline__ float frsq(float x) { return __builtin_amdgcn_rsqf(x); }
; __device__ __forceinline__ float siluf_(float x) { return x * sigmoidf_(x); }
; __device__ __forceinline__ void gla_seq_unit(LAS unsigned char* lds, int b, int h, unsigned char* ws, const float* o_norm, bool dry) {
;     ...
;         for (int mt = 0; mt < 8; ++mt) {
;             const f32x4 dec = *(const LAS f32x4*)(DECL + mt * 16 + fq * 4);
;             f32x4 u0, u1; u0[0] = bflo(ucp[mt].x); u0[1] = bfhi(ucp[mt].x); u0[2] = bflo(ucp[mt].y); u0[3] = bfhi(ucp[mt].y); u1[0] = bflo(ucp[mt].z); u1[1] = bfhi(ucp[mt].z); u1[2] = bflo(ucp[mt].w); u1[3] = bfhi(ucp[mt].w);
;             S[mt][0] = S[mt][0] * dec + u0; S[mt][1] = S[mt][1] * dec + u1;
;         }
;         asm volatile("" ::: "memory");
;         { const bf16_t* UCn = UC + ((ci + 1 < 32) ? 32768 : 0);
; #pragma unroll
;           for (int mt = 0; mt < 6; ++mt) ucp[mt] = *(const u32x4*)(UCn + ((wid * 8 + mt) * 64 + lane) * 8); }
; #pragma unroll
;         for (int tt = 0; tt < 4; ++tt) {
;             float p = 0.f;
; #pragma unroll
;             for (int vt = 0; vt < 2; ++vt)
; #pragma unroll
;                 for (int e = 0; e < 4; ++e) p += o[vt][tt][e] * o[vt][tt][e];
;             p += __shfl_xor(p, 16); p += __shfl_xor(p, 32);
;             if (fq == 0) PART[wid * 64 + tt * 16 + fr] = p;
;         }
;         __syncthreads();
; #pragma unroll
;         for (int tt = 0; tt < 4; ++tt) {
;             const int t = tt * 16 + fr; float tot = 0.f;
; #pragma unroll
;             for (int w = 0; w < 8; ++w) tot += PART[w * 64 + t];
;             const float rs = frsq(tot * (1.f / 256.f) + EPS);
; #pragma unroll
;             for (int vt = 0; vt < 2; ++vt) {
;                 const int vcol = 32 * wid + vt * 16 + fq * 4;
;                 bf16_t* rp = GR + (size_t)(rc + t) * 1024 + h * 256 + vcol;
;                 const u32x2 rr = rr8[tt][vt]; const f32x4 on = *(const f32x4*)(o_norm + h * 256 + vcol);
;                 u32x2 w; w.x = cvt_pk_bf16(o[vt][tt][0] * rs * on[0] * siluf_(bflo(rr.x)), o[vt][tt][1] * rs * on[1] * siluf_(bfhi(rr.x)));
.LBB0_286:
	s_or_b64 exec, exec, s[2:3]
	s_waitcnt lgkmcnt(0)
	v_lshlrev_b32_e32 v252, 16, v68
	v_and_b32_e32 v253, 0xffff0000, v68
	v_lshlrev_b32_e32 v68, 16, v69
	v_and_b32_e32 v69, 0xffff0000, v69
	v_lshlrev_b32_e32 v166, 16, v70
	v_and_b32_e32 v167, 0xffff0000, v70
	v_lshlrev_b32_e32 v70, 16, v71
	v_and_b32_e32 v71, 0xffff0000, v71
	v_pk_fma_f32 v[146:147], v[146:147], v[118:119], v[68:69]
	v_pk_fma_f32 v[142:143], v[142:143], v[118:119], v[70:71]
	v_lshlrev_b32_e32 v68, 16, v64
	v_and_b32_e32 v69, 0xffff0000, v64
	v_lshlrev_b32_e32 v64, 16, v65
	v_and_b32_e32 v65, 0xffff0000, v65
	v_lshlrev_b32_e32 v70, 16, v66
	v_and_b32_e32 v71, 0xffff0000, v66
	v_lshlrev_b32_e32 v66, 16, v67
	v_and_b32_e32 v67, 0xffff0000, v67
	v_pk_fma_f32 v[150:151], v[150:151], v[114:115], v[64:65]
	v_pk_fma_f32 v[154:155], v[154:155], v[114:115], v[66:67]
	v_lshlrev_b32_e32 v64, 16, v60
	v_and_b32_e32 v65, 0xffff0000, v60
	v_lshlrev_b32_e32 v66, 16, v62
	v_and_b32_e32 v67, 0xffff0000, v62
	v_pk_fma_f32 v[156:157], v[156:157], v[108:109], v[64:65]
	v_pk_fma_f32 v[170:171], v[170:171], v[108:109], v[66:67]
	s_barrier
	s_nop 1
	v_mov_b64_e32 v[64:65], v[162:163]
	v_mov_b64_e32 v[66:67], v[164:165]
	v_lshlrev_b32_e32 v60, 16, v61
	v_and_b32_e32 v61, 0xffff0000, v61
	v_lshlrev_b32_e32 v62, 16, v63
	v_and_b32_e32 v63, 0xffff0000, v63
	v_pk_fma_f32 v[158:159], v[158:159], v[110:111], v[60:61]
	v_lshlrev_b32_e32 v60, 16, v52
	v_and_b32_e32 v61, 0xffff0000, v52
	v_lshlrev_b32_e32 v52, 16, v53
	v_and_b32_e32 v53, 0xffff0000, v53
	v_pk_fma_f32 v[172:173], v[172:173], v[110:111], v[62:63]
	v_lshlrev_b32_e32 v62, 16, v54
	v_and_b32_e32 v63, 0xffff0000, v54
	v_lshlrev_b32_e32 v54, 16, v55
	v_and_b32_e32 v55, 0xffff0000, v55
	v_pk_fma_f32 v[176:177], v[176:177], v[106:107], v[52:53]
	v_lshlrev_b32_e32 v52, 16, v56
	v_and_b32_e32 v53, 0xffff0000, v56
	v_pk_fma_f32 v[180:181], v[180:181], v[106:107], v[54:55]
	v_lshlrev_b32_e32 v54, 16, v57
	v_and_b32_e32 v55, 0xffff0000, v57
	v_pk_fma_f32 v[182:183], v[182:183], v[100:101], v[52:53]
	v_lshlrev_b32_e32 v52, 16, v44
	v_and_b32_e32 v53, 0xffff0000, v44
	v_lshlrev_b32_e32 v44, 16, v45
	v_and_b32_e32 v45, 0xffff0000, v45
	v_pk_fma_f32 v[184:185], v[184:185], v[102:103], v[54:55]
	v_lshlrev_b32_e32 v54, 16, v46
	v_and_b32_e32 v55, 0xffff0000, v46
	v_lshlrev_b32_e32 v46, 16, v47
	v_and_b32_e32 v47, 0xffff0000, v47
	v_pk_fma_f32 v[192:193], v[192:193], v[98:99], v[44:45]
	v_lshlrev_b32_e32 v44, 16, v84
	v_and_b32_e32 v45, 0xffff0000, v84
	v_pk_fma_f32 v[196:197], v[196:197], v[98:99], v[46:47]
	v_lshlrev_b32_e32 v46, 16, v85
	v_and_b32_e32 v47, 0xffff0000, v85
	v_pk_fma_f32 v[198:199], v[198:199], v[92:93], v[44:45]
	v_lshlrev_b32_e32 v44, 16, v80
	v_and_b32_e32 v45, 0xffff0000, v80
	v_pk_fma_f32 v[190:191], v[190:191], v[96:97], v[52:53]
	v_lshlrev_b32_e32 v52, 16, v86
	v_and_b32_e32 v53, 0xffff0000, v86
	v_pk_fma_f32 v[200:201], v[200:201], v[94:95], v[46:47]
	v_lshlrev_b32_e32 v46, 16, v81
	v_and_b32_e32 v47, 0xffff0000, v81
	v_pk_fma_f32 v[206:207], v[206:207], v[88:89], v[44:45]
	ds_read2_b32 v[44:45], v245 offset1:16
	v_pk_fma_f32 v[194:195], v[194:195], v[96:97], v[54:55]
	v_lshlrev_b32_e32 v54, 16, v87
	v_and_b32_e32 v55, 0xffff0000, v87
	v_pk_fma_f32 v[202:203], v[202:203], v[92:93], v[52:53]
	v_lshlrev_b32_e32 v52, 16, v82
	v_and_b32_e32 v53, 0xffff0000, v82
	v_pk_fma_f32 v[208:209], v[208:209], v[90:91], v[46:47]
	ds_read2_b32 v[46:47], v245 offset0:64 offset1:80
	v_pk_fma_f32 v[204:205], v[204:205], v[94:95], v[54:55]
	v_lshlrev_b32_e32 v54, 16, v83
	v_and_b32_e32 v55, 0xffff0000, v83
	v_pk_fma_f32 v[210:211], v[210:211], v[88:89], v[52:53]
	ds_read2_b32 v[52:53], v245 offset0:128 offset1:144
	v_pk_fma_f32 v[212:213], v[212:213], v[90:91], v[54:55]
	ds_read2_b32 v[54:55], v245 offset0:192 offset1:208
	s_waitcnt lgkmcnt(3)
	v_add_f32_e32 v44, 0, v44
	s_waitcnt lgkmcnt(2)
	v_add_f32_e32 v44, v44, v46
	v_pk_fma_f32 v[148:149], v[148:149], v[112:113], v[68:69]
	s_waitcnt lgkmcnt(1)
	v_add_f32_e32 v44, v44, v52
	v_lshlrev_b32_e32 v68, 16, v236
	v_lshlrev_b32_e32 v56, 16, v58
	v_and_b32_e32 v57, 0xffff0000, v58
	s_waitcnt lgkmcnt(0)
	v_add_f32_e32 v44, v44, v54
	v_add_u32_e32 v54, 0x400, v245
	v_mul_f32_e32 v46, 0xbfb8aa3b, v68
	v_lshlrev_b32_e32 v58, 16, v59
	v_and_b32_e32 v59, 0xffff0000, v59
	v_pk_fma_f32 v[186:187], v[186:187], v[100:101], v[56:57]
	ds_read2_b32 v[56:57], v54 offset1:16
	v_exp_f32_e32 v46, v46
	v_pk_fma_f32 v[188:189], v[188:189], v[102:103], v[58:59]
	ds_read2_b32 v[58:59], v54 offset0:64 offset1:80
	v_pk_fma_f32 v[174:175], v[174:175], v[104:105], v[60:61]
	ds_read2_b32 v[60:61], v54 offset0:128 offset1:144
	v_pk_fma_f32 v[178:179], v[178:179], v[104:105], v[62:63]
	ds_read2_b32 v[62:63], v54 offset0:192 offset1:208
	v_and_b32_e32 v69, 0xffff0000, v236
	v_add_f32_e32 v46, 1.0, v46
	v_pk_fma_f32 v[152:153], v[152:153], v[112:113], v[70:71]
	s_waitcnt lgkmcnt(3)
	v_add_f32_e32 v44, v44, v56
	v_rcp_f32_e32 v70, v46
	v_mul_f32_e32 v46, 0xbfb8aa3b, v69
	s_waitcnt lgkmcnt(2)
	v_add_f32_e32 v44, v44, v58
	v_exp_f32_e32 v46, v46
	s_waitcnt lgkmcnt(1)
	v_add_f32_e32 v44, v44, v60
	s_waitcnt lgkmcnt(0)
; __device__ __forceinline__ unsigned cvt_pk_bf16(float lo, float hi) { const f32x2_t v = {lo, hi}; const bf16x2_t b = __builtin_convertvector(v, bf16x2_t); return __builtin_bit_cast(unsigned, b); }
; __device__ __forceinline__ float frsq(float x) { return __builtin_amdgcn_rsqf(x); }
; __device__ __forceinline__ float siluf_(float x) { return x * sigmoidf_(x); }
; __device__ __forceinline__ void gla_seq_unit(LAS unsigned char* lds, int b, int h, unsigned char* ws, const float* o_norm, bool dry) {
;     ...
;         { const bf16_t* UCn = UC + ((ci + 1 < 32) ? 32768 : 0);
; #pragma unroll
;           for (int mt = 0; mt < 6; ++mt) ucp[mt] = *(const u32x4*)(UCn + ((wid * 8 + mt) * 64 + lane) * 8); }
;     ...
;         for (int tt = 0; tt < 4; ++tt) {
;             const int t = tt * 16 + fr; float tot = 0.f;
; #pragma unroll
;             for (int w = 0; w < 8; ++w) tot += PART[w * 64 + t];
;             const float rs = frsq(tot * (1.f / 256.f) + EPS);
; #pragma unroll
;             for (int vt = 0; vt < 2; ++vt) {
;                 const int vcol = 32 * wid + vt * 16 + fq * 4;
;                 bf16_t* rp = GR + (size_t)(rc + t) * 1024 + h * 256 + vcol;
;                 const u32x2 rr = rr8[tt][vt]; const f32x4 on = *(const f32x4*)(o_norm + h * 256 + vcol);
;                 u32x2 w; w.x = cvt_pk_bf16(o[vt][tt][0] * rs * on[0] * siluf_(bflo(rr.x)), o[vt][tt][1] * rs * on[1] * siluf_(bfhi(rr.x)));
;                 w.y = cvt_pk_bf16(o[vt][tt][2] * rs * on[2] * siluf_(bflo(rr.y)), o[vt][tt][3] * rs * on[3] * siluf_(bfhi(rr.y)));
;                 if (!dry) *(u32x2*)rp = w;
	v_add_f32_e32 v44, v44, v62
	v_fmamk_f32 v44, v44, 0x3b800000, v239
	v_rsq_f32_e32 v44, v44
	v_add_f32_e32 v46, 1.0, v46
	v_rcp_f32_e32 v71, v46
	v_lshlrev_b32_e32 v60, 16, v224
	v_pk_mul_f32 v[76:77], v[76:77], v[44:45] op_sel_hi:[1,0]
	v_pk_mul_f32 v[72:73], v[72:73], v[44:45] op_sel_hi:[1,0]
	v_pk_mul_f32 v[64:65], v[64:65], v[76:77]
	v_pk_mul_f32 v[68:69], v[70:71], v[68:69]
	v_pk_mul_f32 v[76:77], v[78:79], v[44:45] op_sel_hi:[1,0]
	v_pk_mul_f32 v[64:65], v[68:69], v[64:65]
	v_pk_mul_f32 v[66:67], v[66:67], v[76:77]
	v_cvt_pk_bf16_f32 v68, v64, v65
	v_lshlrev_b32_e32 v64, 16, v237
	v_mul_f32_e32 v46, 0xbfb8aa3b, v64
	v_exp_f32_e32 v46, v46
	v_and_b32_e32 v65, 0xffff0000, v237
	v_pk_mul_f32 v[74:75], v[74:75], v[44:45] op_sel_hi:[1,0]
	s_mov_b64 s[2:3], 0x200
	v_add_f32_e32 v46, 1.0, v46
	v_rcp_f32_e32 v70, v46
	v_mul_f32_e32 v46, 0xbfb8aa3b, v65
	v_exp_f32_e32 v46, v46
	s_add_i32 s10, s10, 64
	v_lshl_add_u64 v[126:127], v[126:127], 0, s[2:3]
	s_mov_b64 s[2:3], 0x8000
	v_add_f32_e32 v46, 1.0, v46
	v_rcp_f32_e32 v71, v46
	v_pk_fma_f32 v[144:145], v[144:145], v[116:117], v[252:253]
	v_pk_fma_f32 v[140:141], v[140:141], v[116:117], v[166:167]
	v_lshl_add_u64 v[128:129], v[128:129], 0, s[30:31]
	v_pk_mul_f32 v[64:65], v[70:71], v[64:65]
	v_lshlrev_b32_e32 v70, 16, v232
	v_pk_mul_f32 v[64:65], v[64:65], v[66:67]
	v_mul_f32_e32 v46, 0xbfb8aa3b, v70
	v_cvt_pk_bf16_f32 v69, v64, v65
	v_lshl_add_u64 v[64:65], v[124:125], 0, v[234:235]
	global_store_dwordx2 v[64:65], v[68:69], off
	s_nop 1
	v_mov_b64_e32 v[66:67], v[168:169]
	v_mov_b64_e32 v[68:69], v[242:243]
	v_exp_f32_e32 v46, v46
	v_and_b32_e32 v71, 0xffff0000, v232
	v_lshl_add_u64 v[130:131], v[130:131], 0, s[30:31]
	v_lshl_add_u64 v[132:133], v[132:133], 0, s[42:43]
	v_add_f32_e32 v46, 1.0, v46
	v_rcp_f32_e32 v76, v46
	v_mul_f32_e32 v46, 0xbfb8aa3b, v71
	v_exp_f32_e32 v46, v46
	v_lshl_add_u64 v[134:135], v[134:135], 0, s[42:43]
	v_lshl_add_u64 v[136:137], v[136:137], 0, s[42:43]
	v_lshl_add_u64 v[138:139], v[138:139], 0, s[2:3]
	v_add_f32_e32 v46, 1.0, v46
	v_rcp_f32_e32 v77, v46
	s_cmpk_eq_i32 s10, 0x800
	v_pk_mul_f32 v[70:71], v[76:77], v[70:71]
	v_pk_mul_f32 v[66:67], v[66:67], v[72:73]
	s_nop 0
	v_pk_mul_f32 v[66:67], v[70:71], v[66:67]
	v_lshlrev_b32_e32 v70, 16, v233
	v_and_b32_e32 v71, 0xffff0000, v233
	v_mul_f32_e32 v46, 0xbfb8aa3b, v70
	v_mul_f32_e32 v44, 0xbfb8aa3b, v71
	v_exp_f32_e32 v46, v46
	v_exp_f32_e32 v44, v44
	v_pk_mul_f32 v[68:69], v[68:69], v[74:75]
	v_cvt_pk_bf16_f32 v66, v66, v67
	v_add_f32_e32 v46, 1.0, v46
	v_add_f32_e32 v44, 1.0, v44
	v_rcp_f32_e32 v72, v46
	v_rcp_f32_e32 v73, v44
	v_add_f32_e32 v44, 0, v45
	v_add_f32_e32 v44, v44, v47
	v_add_f32_e32 v44, v44, v53
	v_pk_mul_f32 v[70:71], v[72:73], v[70:71]
	v_add_f32_e32 v44, v44, v55
	v_pk_mul_f32 v[68:69], v[70:71], v[68:69]
	v_add_f32_e32 v44, v44, v57
	v_cvt_pk_bf16_f32 v67, v68, v69
	global_store_dwordx2 v[64:65], v[66:67], off offset:32
	v_add_f32_e32 v44, v44, v59
	s_nop 1
	v_mov_b64_e32 v[56:57], v[162:163]
	v_mov_b64_e32 v[58:59], v[164:165]
	v_add_f32_e32 v44, v44, v61
	v_lshlrev_b32_e32 v46, 16, v230
	v_add_f32_e32 v44, v44, v63
	v_mul_f32_e32 v45, 0xbfb8aa3b, v46
	v_fmamk_f32 v44, v44, 0x3b800000, v239
	v_exp_f32_e32 v45, v45
	v_rsq_f32_e32 v44, v44
	v_and_b32_e32 v47, 0xffff0000, v230
	v_and_b32_e32 v61, 0xffff0000, v224
	v_add_f32_e32 v45, 1.0, v45
	v_rcp_f32_e32 v52, v45
	v_pk_mul_f32 v[48:49], v[48:49], v[44:45] op_sel_hi:[1,0]
	v_mul_f32_e32 v45, 0xbfb8aa3b, v47
	v_exp_f32_e32 v45, v45
	s_waitcnt vmcnt(6)
	v_mov_b64_e32 v[66:67], v[6:7]
	v_mov_b64_e32 v[70:71], v[2:3]
	v_mov_b64_e32 v[64:65], v[4:5]
	v_add_f32_e32 v45, 1.0, v45
	v_rcp_f32_e32 v53, v45
	v_mov_b64_e32 v[68:69], v[0:1]
	v_pk_mul_f32 v[46:47], v[52:53], v[46:47]
	v_pk_mul_f32 v[48:49], v[56:57], v[48:49]
	s_nop 0
	v_pk_mul_f32 v[46:47], v[46:47], v[48:49]
	v_lshlrev_b32_e32 v48, 16, v231
	v_mul_f32_e32 v45, 0xbfb8aa3b, v48
	v_exp_f32_e32 v45, v45
	v_and_b32_e32 v49, 0xffff0000, v231
	v_cvt_pk_bf16_f32 v46, v46, v47
	v_add_f32_e32 v45, 1.0, v45
	v_rcp_f32_e32 v52, v45
	v_pk_mul_f32 v[50:51], v[50:51], v[44:45] op_sel_hi:[1,0]
	v_mul_f32_e32 v45, 0xbfb8aa3b, v49
	v_exp_f32_e32 v45, v45
	v_pk_mul_f32 v[50:51], v[58:59], v[50:51]
	v_add_f32_e32 v45, 1.0, v45
	v_rcp_f32_e32 v53, v45
	s_nop 0
	v_pk_mul_f32 v[48:49], v[52:53], v[48:49]
	s_nop 0
	v_pk_mul_f32 v[48:49], v[48:49], v[50:51]
	v_lshl_add_u64 v[50:51], v[124:125], 0, v[228:229]
	v_cvt_pk_bf16_f32 v47, v48, v49
	global_store_dwordx2 v[50:51], v[46:47], off
	s_nop 1
	v_mov_b64_e32 v[46:47], v[168:169]
	v_mov_b64_e32 v[48:49], v[242:243]
	v_lshlrev_b32_e32 v52, 16, v226
	v_mul_f32_e32 v45, 0xbfb8aa3b, v52
	v_exp_f32_e32 v45, v45
	v_and_b32_e32 v53, 0xffff0000, v226
	v_add_f32_e32 v45, 1.0, v45
	v_rcp_f32_e32 v56, v45
	v_pk_mul_f32 v[40:41], v[40:41], v[44:45] op_sel_hi:[1,0]
	v_mul_f32_e32 v45, 0xbfb8aa3b, v53
	v_exp_f32_e32 v45, v45
	v_pk_mul_f32 v[40:41], v[46:47], v[40:41]
	v_add_f32_e32 v45, 1.0, v45
	v_rcp_f32_e32 v57, v45
	v_pk_mul_f32 v[42:43], v[42:43], v[44:45] op_sel_hi:[1,0]
	v_pk_mul_f32 v[46:47], v[56:57], v[52:53]
	s_nop 0
	v_pk_mul_f32 v[40:41], v[46:47], v[40:41]
	v_lshlrev_b32_e32 v46, 16, v227
	v_cvt_pk_bf16_f32 v40, v40, v41
	v_mul_f32_e32 v41, 0xbfb8aa3b, v46
	v_exp_f32_e32 v41, v41
	v_and_b32_e32 v47, 0xffff0000, v227
	v_pk_mul_f32 v[42:43], v[48:49], v[42:43]
	ds_read2_b32 v[48:49], v54 offset0:32 offset1:48
	v_add_f32_e32 v41, 1.0, v41
	v_rcp_f32_e32 v52, v41
	v_mul_f32_e32 v41, 0xbfb8aa3b, v47
	v_exp_f32_e32 v41, v41
	s_nop 0
	v_add_f32_e32 v41, 1.0, v41
	v_rcp_f32_e32 v53, v41
	s_nop 0
	v_pk_mul_f32 v[44:45], v[52:53], v[46:47]
	s_nop 0
	v_pk_mul_f32 v[42:43], v[44:45], v[42:43]
	ds_read2_b32 v[44:45], v245 offset0:160 offset1:176
	v_cvt_pk_bf16_f32 v41, v42, v43
	global_store_dwordx2 v[50:51], v[40:41], off offset:32
	s_nop 1
	v_mov_b64_e32 v[56:57], v[162:163]
	v_mov_b64_e32 v[58:59], v[164:165]
	ds_read2_b32 v[40:41], v245 offset0:32 offset1:48
	ds_read2_b32 v[42:43], v245 offset0:96 offset1:112
	ds_read2_b32 v[46:47], v245 offset0:224 offset1:240
	ds_read2_b32 v[50:51], v54 offset0:96 offset1:112
	ds_read2_b32 v[52:53], v54 offset0:160 offset1:176
	s_waitcnt lgkmcnt(4)
; __device__ __forceinline__ unsigned cvt_pk_bf16(float lo, float hi) { const f32x2_t v = {lo, hi}; const bf16x2_t b = __builtin_convertvector(v, bf16x2_t); return __builtin_bit_cast(unsigned, b); }
; __device__ __forceinline__ float frsq(float x) { return __builtin_amdgcn_rsqf(x); }
; __device__ __forceinline__ float siluf_(float x) { return x * sigmoidf_(x); }
; __device__ __forceinline__ void gla_seq_unit(LAS unsigned char* lds, int b, int h, unsigned char* ws, const float* o_norm, bool dry) {
;     ...
;         { const bf16_t* UCn = UC + ((ci + 1 < 32) ? 32768 : 0);
; #pragma unroll
;           for (int mt = 0; mt < 6; ++mt) ucp[mt] = *(const u32x4*)(UCn + ((wid * 8 + mt) * 64 + lane) * 8); }
;     ...
;         for (int tt = 0; tt < 4; ++tt) {
;             const int t = tt * 16 + fr; float tot = 0.f;
; #pragma unroll
;             for (int w = 0; w < 8; ++w) tot += PART[w * 64 + t];
;             const float rs = frsq(tot * (1.f / 256.f) + EPS);
; #pragma unroll
;             for (int vt = 0; vt < 2; ++vt) {
;                 const int vcol = 32 * wid + vt * 16 + fq * 4;
;                 bf16_t* rp = GR + (size_t)(rc + t) * 1024 + h * 256 + vcol;
;                 const u32x2 rr = rr8[tt][vt]; const f32x4 on = *(const f32x4*)(o_norm + h * 256 + vcol);
;                 u32x2 w; w.x = cvt_pk_bf16(o[vt][tt][0] * rs * on[0] * siluf_(bflo(rr.x)), o[vt][tt][1] * rs * on[1] * siluf_(bfhi(rr.x)));
;                 w.y = cvt_pk_bf16(o[vt][tt][2] * rs * on[2] * siluf_(bflo(rr.y)), o[vt][tt][3] * rs * on[3] * siluf_(bfhi(rr.y)));
;                 if (!dry) *(u32x2*)rp = w;
	v_add_f32_e32 v40, 0, v40
	s_waitcnt lgkmcnt(3)
	v_add_f32_e32 v40, v40, v42
	v_mul_f32_e32 v42, 0xbfb8aa3b, v60
	v_exp_f32_e32 v42, v42
	v_add_f32_e32 v40, v40, v44
	ds_read2_b32 v[54:55], v54 offset0:224 offset1:240
	s_waitcnt lgkmcnt(3)
	v_add_f32_e32 v40, v40, v46
	v_add_f32_e32 v42, 1.0, v42
	v_add_f32_e32 v40, v40, v48
	v_rcp_f32_e32 v62, v42
	v_mul_f32_e32 v42, 0xbfb8aa3b, v61
	s_waitcnt lgkmcnt(2)
	v_add_f32_e32 v40, v40, v50
	v_exp_f32_e32 v42, v42
	s_waitcnt lgkmcnt(1)
	v_add_f32_e32 v40, v40, v52
	s_waitcnt lgkmcnt(0)
	v_add_f32_e32 v40, v40, v54
	v_fmamk_f32 v40, v40, 0x3b800000, v239
	v_rsq_f32_e32 v40, v40
	v_add_f32_e32 v42, 1.0, v42
	v_rcp_f32_e32 v63, v42
	v_pk_mul_f32 v[36:37], v[36:37], v[40:41] op_sel_hi:[1,0]
	v_pk_mul_f32 v[38:39], v[38:39], v[40:41] op_sel_hi:[1,0]
	v_pk_mul_f32 v[32:33], v[32:33], v[40:41] op_sel_hi:[1,0]
	v_pk_mul_f32 v[34:35], v[34:35], v[40:41] op_sel_hi:[1,0]
	v_pk_mul_f32 v[36:37], v[56:57], v[36:37]
	v_pk_mul_f32 v[56:57], v[62:63], v[60:61]
	v_pk_mul_f32 v[38:39], v[58:59], v[38:39]
	v_pk_mul_f32 v[36:37], v[56:57], v[36:37]
	s_nop 0
	v_cvt_pk_bf16_f32 v56, v36, v37
	v_lshlrev_b32_e32 v36, 16, v225
	v_mul_f32_e32 v42, 0xbfb8aa3b, v36
	v_exp_f32_e32 v42, v42
	v_and_b32_e32 v37, 0xffff0000, v225
	v_add_f32_e32 v42, 1.0, v42
	v_rcp_f32_e32 v60, v42
	v_mul_f32_e32 v42, 0xbfb8aa3b, v37
	v_exp_f32_e32 v42, v42
	s_nop 0
	v_add_f32_e32 v42, 1.0, v42
	v_rcp_f32_e32 v61, v42
	s_nop 0
	v_pk_mul_f32 v[36:37], v[60:61], v[36:37]
	s_nop 0
	v_pk_mul_f32 v[36:37], v[36:37], v[38:39]
	v_lshlrev_b32_e32 v38, 16, v220
	v_cvt_pk_bf16_f32 v57, v36, v37
	v_lshl_add_u64 v[36:37], v[124:125], 0, v[222:223]
	global_store_dwordx2 v[36:37], v[56:57], off
	s_nop 1
	v_mov_b64_e32 v[56:57], v[168:169]
	v_mov_b64_e32 v[58:59], v[242:243]
	v_mul_f32_e32 v42, 0xbfb8aa3b, v38
	v_exp_f32_e32 v42, v42
	v_and_b32_e32 v39, 0xffff0000, v220
	v_add_f32_e32 v42, 1.0, v42
	v_rcp_f32_e32 v60, v42
	v_mul_f32_e32 v42, 0xbfb8aa3b, v39
	v_exp_f32_e32 v42, v42
	v_pk_mul_f32 v[32:33], v[56:57], v[32:33]
	v_add_f32_e32 v42, 1.0, v42
	v_rcp_f32_e32 v61, v42
	v_pk_mul_f32 v[34:35], v[58:59], v[34:35]
	v_pk_mul_f32 v[38:39], v[60:61], v[38:39]
	s_nop 0
	v_pk_mul_f32 v[32:33], v[38:39], v[32:33]
	v_lshlrev_b32_e32 v38, 16, v221
	v_cvt_pk_bf16_f32 v32, v32, v33
	v_mul_f32_e32 v33, 0xbfb8aa3b, v38
	v_exp_f32_e32 v33, v33
	v_and_b32_e32 v39, 0xffff0000, v221
	s_waitcnt vmcnt(8)
	v_mov_b64_e32 v[62:63], v[10:11]
	v_mov_b64_e32 v[60:61], v[8:9]
	v_add_f32_e32 v33, 1.0, v33
	v_rcp_f32_e32 v56, v33
	v_mul_f32_e32 v33, 0xbfb8aa3b, v39
	v_exp_f32_e32 v33, v33
	s_nop 0
	v_add_f32_e32 v33, 1.0, v33
	v_rcp_f32_e32 v57, v33
	s_nop 0
	v_pk_mul_f32 v[38:39], v[56:57], v[38:39]
	s_nop 0
	v_pk_mul_f32 v[34:35], v[38:39], v[34:35]
	v_lshlrev_b32_e32 v38, 16, v218
	v_cvt_pk_bf16_f32 v33, v34, v35
	global_store_dwordx2 v[36:37], v[32:33], off offset:32
	v_add_f32_e32 v32, 0, v41
	v_add_f32_e32 v32, v32, v43
	v_add_f32_e32 v32, v32, v45
	v_add_f32_e32 v32, v32, v47
	v_add_f32_e32 v32, v32, v49
	v_add_f32_e32 v32, v32, v51
	v_add_f32_e32 v32, v32, v53
	v_add_f32_e32 v32, v32, v55
	v_fmamk_f32 v32, v32, 0x3b800000, v239
	v_rsq_f32_e32 v36, v32
	s_nop 1
	v_mov_b64_e32 v[32:33], v[162:163]
	v_mov_b64_e32 v[34:35], v[164:165]
	v_mul_f32_e32 v37, 0xbfb8aa3b, v38
	v_exp_f32_e32 v37, v37
	v_and_b32_e32 v39, 0xffff0000, v218
	s_waitcnt vmcnt(6)
	v_mov_b64_e32 v[46:47], v[22:23]
	v_mov_b64_e32 v[58:59], v[18:19]
	v_add_f32_e32 v37, 1.0, v37
	v_pk_mul_f32 v[28:29], v[28:29], v[36:37] op_sel_hi:[1,0]
	v_rcp_f32_e32 v40, v37
	v_pk_mul_f32 v[30:31], v[30:31], v[36:37] op_sel_hi:[1,0]
	v_mov_b64_e32 v[54:55], v[14:15]
	v_mov_b64_e32 v[44:45], v[20:21]
	v_mov_b64_e32 v[56:57], v[16:17]
	v_mov_b64_e32 v[52:53], v[12:13]
	v_pk_mul_f32 v[28:29], v[32:33], v[28:29]
	v_mul_f32_e32 v32, 0xbfb8aa3b, v39
	v_exp_f32_e32 v32, v32
	v_pk_mul_f32 v[30:31], v[34:35], v[30:31]
	v_lshlrev_b32_e32 v34, 16, v214
	v_mul_f32_e32 v37, 0xbfb8aa3b, v34
	v_add_f32_e32 v32, 1.0, v32
	v_rcp_f32_e32 v41, v32
	v_exp_f32_e32 v37, v37
	v_and_b32_e32 v35, 0xffff0000, v214
	v_pk_mul_f32 v[32:33], v[40:41], v[38:39]
	s_nop 0
	v_pk_mul_f32 v[28:29], v[32:33], v[28:29]
	v_lshlrev_b32_e32 v32, 16, v219
	v_cvt_pk_bf16_f32 v28, v28, v29
	v_mul_f32_e32 v29, 0xbfb8aa3b, v32
	v_exp_f32_e32 v29, v29
	v_and_b32_e32 v33, 0xffff0000, v219
	v_add_f32_e32 v37, 1.0, v37
	v_pk_mul_f32 v[24:25], v[24:25], v[36:37] op_sel_hi:[1,0]
	v_add_f32_e32 v29, 1.0, v29
	v_rcp_f32_e32 v38, v29
	v_mul_f32_e32 v29, 0xbfb8aa3b, v33
	v_exp_f32_e32 v29, v29
	v_pk_mul_f32 v[26:27], v[26:27], v[36:37] op_sel_hi:[1,0]
	v_add_f32_e32 v29, 1.0, v29
	v_rcp_f32_e32 v39, v29
	s_nop 0
	v_pk_mul_f32 v[32:33], v[38:39], v[32:33]
	s_nop 0
	v_pk_mul_f32 v[30:31], v[32:33], v[30:31]
	v_lshl_add_u64 v[32:33], v[124:125], 0, v[216:217]
	v_cvt_pk_bf16_f32 v29, v30, v31
	global_store_dwordx2 v[32:33], v[28:29], off
	s_nop 1
	v_mov_b64_e32 v[28:29], v[168:169]
	v_mov_b64_e32 v[30:31], v[242:243]
	v_rcp_f32_e32 v38, v37
	v_pk_mul_f32 v[24:25], v[28:29], v[24:25]
	v_mul_f32_e32 v28, 0xbfb8aa3b, v35
	v_exp_f32_e32 v28, v28
	v_pk_mul_f32 v[26:27], v[30:31], v[26:27]
	v_add_f32_e32 v28, 1.0, v28
	v_rcp_f32_e32 v39, v28
	s_nop 0
	v_pk_mul_f32 v[28:29], v[38:39], v[34:35]
	s_nop 0
	v_pk_mul_f32 v[24:25], v[28:29], v[24:25]
	v_lshlrev_b32_e32 v28, 16, v215
	v_cvt_pk_bf16_f32 v24, v24, v25
	v_mul_f32_e32 v25, 0xbfb8aa3b, v28
	v_exp_f32_e32 v25, v25
	v_and_b32_e32 v29, 0xffff0000, v215
	v_add_f32_e32 v25, 1.0, v25
	v_rcp_f32_e32 v34, v25
	v_mul_f32_e32 v25, 0xbfb8aa3b, v29
	v_exp_f32_e32 v25, v25
	s_nop 0
	v_add_f32_e32 v25, 1.0, v25
	v_rcp_f32_e32 v35, v25
	s_nop 0
	v_pk_mul_f32 v[28:29], v[34:35], v[28:29]
	s_nop 0
	v_pk_mul_f32 v[26:27], v[28:29], v[26:27]
	s_nop 0
	v_cvt_pk_bf16_f32 v25, v26, v27
	global_store_dwordx2 v[32:33], v[24:25], off offset:32
	s_cbranch_scc1 .LBB0_297

; __global__ void __launch_bounds__(NTHREADS, 2) fwd_kernel(Args a) {
;     ...
;                 if (bx < 32) { gla_seq_unit(lds, bx >> 2, bx & 3, ws, AIN(14) + l * 1024, dry); }
.LBB0_297:
	v_mov_b64_e32 v[162:163], 0x200
	v_mov_b64_e32 v[164:165], 0x1ff
	v_mov_b64_e32 v[168:169], 0xda25000
	v_mov_b32_e32 v242, 1
	v_mov_b32_e32 v243, 0xff800000
	s_mov_b64 s[2:3], 0
